# speedup vs baseline: 1.0021x; 1.0021x over previous
;     __host__ __device__ bool next(int i, Unit& u) const {
;         const long L = (long)i * G + c; if (L >= nwg) return false;
;         int wgid = (int)L; { const int q = nwg / NXCD, r = nwg % NXCD, xcd = wgid % NXCD, off = wgid / NXCD; wgid = (xcd < r ? xcd * (q + 1) : r * (q + 1) + (xcd - r) * q) + off; }
;         const int nig = WGM * nN, gid = wgid / nig, fm = gid * WGM, gsz = (nM - fm) < WGM ? (nM - fm) : WGM;
;         u.pm = fm + ((wgid % nig) % gsz); u.pn = (wgid % nig) / gsz; return true;
; template <class Epi, class Sched, bool ALIGN_EPI = false, bool SP2 = false>
; __device__ __forceinline__ void gemm_phase(PG8_LAS unsigned char* lds, const Gemm g, const Sched& S, const Epi& E, const int tid) {
;     ...
;     if (!S.next(0, cur)) return;
.LBB0_597:
	s_mov_b32 s62, s90
	s_mul_i32 s20, s30, s61
	s_mov_b32 s98, s88
	s_mov_b32 s99, s20
	s_cmp_lg_u32 s20, 0x400
	s_cbranch_scc1 .Lmy_j0
	s_movk_i32 s98, 0xe0
	s_cmp_lt_u32 s62, 32
	s_cbranch_scc1 .Lmy_jc
	s_sub_u32 s62, s62, 32
	s_movk_i32 s99, 0x3e0
	s_branch .Lmy_j0
.Lmy_jc:
	s_add_u32 s62, s62, 0x3e0
.Lmy_j0:
	s_cmp_lt_i32 s62, s20
	s_cselect_b64 s[24:25], -1, 0
	s_cmp_ge_i32 s62, s20
	v_readfirstlane_b32 s21, v213
	s_cbranch_scc1 .LBB0_604
	s_ashr_i32 s10, s62, 31
	s_lshr_b32 s10, s10, 29
	s_add_i32 s26, s62, s10
	s_lshr_b32 s35, s20, 3
	s_and_b32 s10, s26, -8
	s_and_b32 s36, s20, 4
	s_sub_i32 s31, s62, s10
	s_add_i32 s34, s35, 1
	s_cmp_ge_i32 s31, s36
	s_mov_b64 s[10:11], -1
	s_cbranch_scc0 .LBB0_600
	s_sub_i32 s11, s31, s36
	s_mul_i32 s10, s34, s36
	s_mul_i32 s11, s11, s35
	s_add_i32 s27, s11, s10
	s_mov_b64 s[10:11], 0

;     __host__ __device__ bool next(int i, Unit& u) const {
;         const long L = (long)i * G + c; if (L >= nwg) return false;
;         int wgid = (int)L; { const int q = nwg / NXCD, r = nwg % NXCD, xcd = wgid % NXCD, off = wgid / NXCD; wgid = (xcd < r ? xcd * (q + 1) : r * (q + 1) + (xcd - r) * q) + off; }
;         const int nig = WGM * nN, gid = wgid / nig, fm = gid * WGM, gsz = (nM - fm) < WGM ? (nM - fm) : WGM;
;         u.pm = fm + ((wgid % nig) % gsz); u.pn = (wgid % nig) / gsz; return true;
; template <class Epi, class Sched, bool ALIGN_EPI = false, bool SP2 = false>
; __device__ __forceinline__ void gemm_phase(PG8_LAS unsigned char* lds, const Gemm g, const Sched& S, const Epi& E, const int tid) {
;     ...
;         const bool has_next = S.next(ui + 1, nxt);
.LBB0_610:
	s_add_i32 s92, s92, 1
	s_mul_i32 s34, s92, s89
	s_mul_hi_u32 s35, s92, s98
	s_add_i32 s35, s35, s34
	s_mul_i32 s34, s92, s98
	s_add_u32 s34, s34, s62
	s_addc_u32 s35, s35, s83
	v_mov_b32_e32 v0, s99
	v_mov_b32_e32 v1, 0
	v_cmp_ge_i64_e32 vcc, s[34:35], v[0:1]
	v_cmp_lt_i64_e64 s[44:45], s[34:35], v[0:1]
	s_cbranch_vccnz .LBB0_616
	s_ashr_i32 s35, s34, 31
	s_lshr_b32 s35, s35, 29
	s_add_i32 s36, s34, s35
	s_and_b32 s35, s36, -8
	s_sub_i32 s37, s34, s35
	s_cmp_ge_i32 s37, s86
	s_mov_b64 s[34:35], -1
	s_cbranch_scc0 .LBB0_613
	s_sub_i32 s34, s37, s86
	s_mul_i32 s34, s34, s85
	s_mul_i32 s35, s87, s86
	s_add_i32 s42, s34, s35
	s_mov_b64 s[34:35], 0
